# v7 with the late weight copies shared 3:2 (GLA:mLSTM) instead of 4:1
# baseline (speedup 1.0000x reference)
; __device__ __forceinline__ void p0_transposes(Frame& F, int it_lo, int it_hi, int gw, int NGW) {
;     ...
;     int it = it_lo + gw; if (it >= it_hi) return;
;     TrItem cur = tr_decode(F, it); f32x4 v[8]; float g[8];
;     tr_load(cur, v, g, lane);
;     for (;;) {
;         const int nx = it + NGW; const bool more = nx < it_hi;
; template <int PH> __device__ __forceinline__ void run_phase(Frame& F, const Args& args) {
;     ...
;             if (F.G == 256 && ((F.vcu >> 4) & 1) == 0) { __syncthreads(); p0_transposes(F, P0_I_W1 + P0_SPLIT, P0_NITEMS, (((F.vcu >> 5) << 4) | (F.vcu & 15)) * NWAVES + F.wave, 128 * NWAVES); }
.LBB0_870:
	v_readlane_b32 s2, v241, 52
	s_bitcmp0_b32 s2, 4
	s_movk_i32 s101, 0x1980
	s_cselect_b32 s100, 0, 0xc00
	s_cselect_b32 s101, 0x1180, s101
	v_readlane_b32 s4, v241, 46
	s_mov_b64 s[0:1], -1
	v_readlane_b32 s5, v241, 47
	s_and_b64 s[0:1], s[4:5], s[0:1]
	v_readlane_b32 s68, v241, 42
	v_readlane_b32 s74, v240, 9
	s_and_b64 vcc, exec, s[0:1]
	v_readlane_b32 s66, v240, 13
	v_readlane_b32 s69, v241, 43
	v_readlane_b32 s70, v241, 50
	v_readlane_b32 s72, v240, 11
	v_readlane_b32 s75, v240, 10
	v_readlane_b32 s67, v240, 8
	v_readlane_b32 s76, v240, 7
	v_readlane_b32 s71, v241, 51
	v_readlane_b32 s73, v240, 12
	s_cbranch_vccz .LBB0_1025
	s_lshr_b32 s0, s2, 1
	s_and_b32 s0, s0, 0x1ffffff0
	s_and_b32 s1, s2, 15
	s_or_b32 s0, s0, s1
	s_lshl_b32 s12, s0, 3
	v_readlane_b32 s0, v241, 48
	s_add_i32 s12, s12, s0
	v_mov_b32_e32 v1, v0
	s_add_i32 s12, s12, s100
	s_cmpk_gt_i32 s12, 0x13ff
	s_barrier
	s_cbranch_scc1 .LBB0_1025
	s_add_i32 s22, s12, 0x980
	s_cmp_gt_i32 s12, -1
	s_cbranch_scc0 .LBB0_878
	s_cmpk_gt_u32 s22, 0xa7f
	s_cbranch_scc0 .LBB0_880
	s_cmpk_gt_u32 s22, 0xb7f
	s_cbranch_scc0 .LBB0_932
	s_cmpk_gt_u32 s22, 0xd7f
	s_cbranch_scc0 .LBB0_933
	s_lshl_b32 s4, s22, 5
	s_cmpk_gt_u32 s22, 0x157f
	s_cbranch_scc0 .LBB0_934
	v_readlane_b32 s36, v241, 18
	s_add_i32 s0, s12, 0xfffff400
	v_readlane_b32 s46, v241, 28
	v_readlane_b32 s47, v241, 29
	s_lshr_b32 s23, s0, 5
	s_and_b32 s24, s4, 0x3e0
	s_mov_b64 s[0:1], 0
	s_mov_b64 s[2:3], 0
	v_readlane_b32 s37, v241, 19
	v_readlane_b32 s38, v241, 20
	v_readlane_b32 s39, v241, 21
	v_readlane_b32 s40, v241, 22
	v_readlane_b32 s41, v241, 23
	v_readlane_b32 s42, v241, 24
	v_readlane_b32 s43, v241, 25
	v_readlane_b32 s44, v241, 26
	v_readlane_b32 s45, v241, 27
	v_readlane_b32 s48, v241, 30
	v_readlane_b32 s49, v241, 31
	v_readlane_b32 s50, v241, 32
	v_readlane_b32 s51, v241, 33
	s_mov_b64 s[6:7], s[46:47]
	s_branch .LBB0_935
